# code placement: the seven hot loop heads (GEMM K loops, both attention loops, PEER u and v sweeps) aligned to 64 bytes
# baseline (speedup 1.0000x reference)
;     __host__ __device__ bool next(int i, Unit& o) const { if (i != 0) return false; o = u; return true; }
; template <class Epi, class Sched, bool ALIGN_EPI = false, bool SP2 = false>
; __device__ __forceinline__ void gemm_phase(PG8_LAS unsigned char* lds, const Gemm g, const Sched& S, const Epi& E) {
;     ...
;         const bool has_next = S.next(ui + 1, nxt);
;         const char* nA = has_next ? (const char*)g.A + (size_t)nxt.pm * tstep : cA; const char* nB = has_next ? (const char*)g.Bt + (size_t)nxt.pn * tstep : cB;
;         for (int t = 0; t < nt; t += 2) {
;             const bool last = (t == nt - 2);
;             const char* a1 = cA + (size_t)(t + 1) * kstep;
;             const char* a2 = last ? nA : cA + (size_t)(t + 2) * kstep; const char* b2 = last ? nB : cB + (size_t)(t + 2) * kstep;
;             const char* a3 = a2 + kstep; const char* b3 = b2 + kstep;
;     ...
; #pragma unroll
;         for (int a = 0; a < 2; ++a)
; #pragma unroll
;             for (int b = 0; b < 2; ++b)
; #pragma unroll
;                 for (int m = 0; m < 4; ++m)
; #pragma unroll
;                     for (int n = 0; n < 2; ++n) acc[a][b][m][n] = (f32x4){0.f, 0.f, 0.f, 0.f};
;         cur = nxt; cA = nA; cB = nB; ++ui;
.LBB0_240:
	s_ashr_i32 s77, s76, 31
	s_lshl_b64 s[10:11], s[76:77], 19
	s_add_u32 s78, s94, s10
	s_addc_u32 s79, s95, s11
	s_and_b64 s[10:11], s[4:5], exec
	s_cselect_b32 s9, s79, s7
	s_cselect_b32 s77, s78, s6
	s_ashr_i32 s75, s74, 31
	s_lshl_b64 s[10:11], s[74:75], 19
	s_add_u32 s80, s58, s10
	s_addc_u32 s81, s59, s11
	s_and_b64 s[10:11], s[4:5], exec
	s_cselect_b32 s75, s81, s83
	s_cselect_b32 s84, s80, s82
	s_add_u32 s6, s6, 0x40080
	s_addc_u32 s7, s7, 0
	s_add_u32 s82, s82, 0x100
	v_mov_b32_e32 v4, 0
	s_addc_u32 s83, s83, 0
	s_mov_b32 s85, -2
	v_mov_b32_e32 v5, v4
	v_mov_b32_e32 v6, v4
	v_mov_b32_e32 v7, v4
	v_mov_b32_e32 v0, v4
	v_mov_b32_e32 v1, v4
	v_mov_b32_e32 v2, v4
	v_mov_b32_e32 v3, v4
	v_mov_b32_e32 v20, v4
	v_mov_b32_e32 v21, v4
	v_mov_b32_e32 v22, v4
	v_mov_b32_e32 v23, v4
	v_mov_b32_e32 v16, v4
	v_mov_b32_e32 v17, v4
	v_mov_b32_e32 v18, v4
	v_mov_b32_e32 v19, v4
	v_mov_b32_e32 v36, v4
	v_mov_b32_e32 v37, v4
	v_mov_b32_e32 v38, v4
	v_mov_b32_e32 v39, v4
	v_mov_b32_e32 v32, v4
	v_mov_b32_e32 v33, v4
	v_mov_b32_e32 v34, v4
	v_mov_b32_e32 v35, v4
	v_mov_b32_e32 v52, v4
	v_mov_b32_e32 v53, v4
	v_mov_b32_e32 v54, v4
	v_mov_b32_e32 v55, v4
	v_mov_b32_e32 v48, v4
	v_mov_b32_e32 v49, v4
	v_mov_b32_e32 v50, v4
	v_mov_b32_e32 v51, v4
	v_mov_b32_e32 v12, v4
	v_mov_b32_e32 v13, v4
	v_mov_b32_e32 v14, v4
	v_mov_b32_e32 v15, v4
	v_mov_b32_e32 v8, v4
	v_mov_b32_e32 v9, v4
	v_mov_b32_e32 v10, v4
	v_mov_b32_e32 v11, v4
	v_mov_b32_e32 v28, v4
	v_mov_b32_e32 v29, v4
	v_mov_b32_e32 v30, v4
	v_mov_b32_e32 v31, v4
	v_mov_b32_e32 v24, v4
	v_mov_b32_e32 v25, v4
	v_mov_b32_e32 v26, v4
	v_mov_b32_e32 v27, v4
	v_mov_b32_e32 v44, v4
	v_mov_b32_e32 v45, v4
	v_mov_b32_e32 v46, v4
	v_mov_b32_e32 v47, v4
	v_mov_b32_e32 v40, v4
	v_mov_b32_e32 v41, v4
	v_mov_b32_e32 v42, v4
	v_mov_b32_e32 v43, v4
	v_mov_b32_e32 v60, v4
	v_mov_b32_e32 v61, v4
	v_mov_b32_e32 v62, v4
	v_mov_b32_e32 v63, v4
	v_mov_b32_e32 v56, v4
	v_mov_b32_e32 v57, v4
	v_mov_b32_e32 v58, v4
	v_mov_b32_e32 v59, v4
	v_mov_b32_e32 v68, v4
	v_mov_b32_e32 v69, v4
	v_mov_b32_e32 v70, v4
	v_mov_b32_e32 v71, v4
	v_mov_b32_e32 v64, v4
	v_mov_b32_e32 v65, v4
	v_mov_b32_e32 v66, v4
	v_mov_b32_e32 v67, v4
	v_mov_b32_e32 v84, v4
	v_mov_b32_e32 v85, v4
	v_mov_b32_e32 v86, v4
	v_mov_b32_e32 v87, v4
	v_mov_b32_e32 v80, v4
	v_mov_b32_e32 v81, v4
	v_mov_b32_e32 v82, v4
	v_mov_b32_e32 v83, v4
	v_mov_b32_e32 v100, v4
	v_mov_b32_e32 v101, v4
	v_mov_b32_e32 v102, v4
	v_mov_b32_e32 v103, v4
	v_mov_b32_e32 v96, v4
	v_mov_b32_e32 v97, v4
	v_mov_b32_e32 v98, v4
	v_mov_b32_e32 v99, v4
	v_mov_b32_e32 v116, v4
	v_mov_b32_e32 v117, v4
	v_mov_b32_e32 v118, v4
	v_mov_b32_e32 v119, v4
	v_mov_b32_e32 v112, v4
	v_mov_b32_e32 v113, v4
	v_mov_b32_e32 v114, v4
	v_mov_b32_e32 v115, v4
	v_mov_b32_e32 v76, v4
	v_mov_b32_e32 v77, v4
	v_mov_b32_e32 v78, v4
	v_mov_b32_e32 v79, v4
	v_mov_b32_e32 v72, v4
	v_mov_b32_e32 v73, v4
	v_mov_b32_e32 v74, v4
	v_mov_b32_e32 v75, v4
	v_mov_b32_e32 v92, v4
	v_mov_b32_e32 v93, v4
	v_mov_b32_e32 v94, v4
	v_mov_b32_e32 v95, v4
	v_mov_b32_e32 v88, v4
	v_mov_b32_e32 v89, v4
	v_mov_b32_e32 v90, v4
	v_mov_b32_e32 v91, v4
	v_mov_b32_e32 v108, v4
	v_mov_b32_e32 v109, v4
	v_mov_b32_e32 v110, v4
	v_mov_b32_e32 v111, v4
	v_mov_b32_e32 v104, v4
	v_mov_b32_e32 v105, v4
	v_mov_b32_e32 v106, v4
	v_mov_b32_e32 v107, v4
	v_mov_b32_e32 v124, v4
	v_mov_b32_e32 v125, v4
	v_mov_b32_e32 v126, v4
	v_mov_b32_e32 v127, v4
	v_mov_b32_e32 v120, v4
	v_mov_b32_e32 v121, v4
	v_mov_b32_e32 v122, v4
	v_mov_b32_e32 v123, v4
	.p2align	6

;     static __device__ __forceinline__ unsigned pk8(float x0, float x1, float x2, float x3) { int w = 0; w = __builtin_amdgcn_cvt_pk_fp8_f32(x0, x1, w, false); w = __builtin_amdgcn_cvt_pk_fp8_f32(x2, x3, w, true); return (unsigned)w; }
; #define EX(v) __builtin_amdgcn_exp2f(v)
; #define WB(n) do { if ((n) == 0) ATT_WAIT_BAR(0); else if ((n) == 1) ATT_WAIT_BAR(1); else if ((n) == 2) ATT_WAIT_BAR(2); else if ((n) == 3) ATT_WAIT_BAR(3); else if ((n) == 4) ATT_WAIT_BAR(4); else if ((n) == 5) ATT_WAIT_BAR(5); else ATT_WAIT_BAR(10); } while (0)
; #define EX(v) __builtin_amdgcn_exp2f(v)
; __device__ __forceinline__ int pk8(int old, float x0, float x1, float x2, float x3) { int w = __builtin_amdgcn_cvt_pk_fp8_f32(x0, x1, old, false); w = __builtin_amdgcn_cvt_pk_fp8_f32(x2, x3, w, true); return w; }
; #define DMA8(t, slot) glds16s(dsrc + (size_t)((t) + dlead) * TS, dvoff, (unsigned)__builtin_amdgcn_readfirstlane(ddst + (slot) * TS))
; #define FRAG(dst, off) do { const i32x4 lo_ = RD16(fb0, off), hi_ = RD16(fb1, off); dst = (i32x8){lo_[0], lo_[1], lo_[2], lo_[3], hi_[0], hi_[1], hi_[2], hi_[3]}; } while (0)
; #define MFQK(a) __builtin_amdgcn_mfma_scale_f32_32x32x64_f8f6f4(a, qf, cb, 0, 0, 0, SC1, 0, SCQ)
; #define EX(v) __builtin_amdgcn_exp2f(v)
; __device__ __forceinline__ void attn_unit_f8(const UnitDesc8& U, char* shm) {
;     ...
;     if (kw) { glds16s(dsrc, dvoff, (unsigned)__builtin_amdgcn_readfirstlane(ddst)); glds16s(dsrc + TS, dvoff, (unsigned)__builtin_amdgcn_readfirstlane(ddst + TS)); glds16s(dsrc + 2 * TS, dvoff, (unsigned)__builtin_amdgcn_readfirstlane(ddst + 2 * TS)); }
;     else { glds16s(dsrc, dvoff, (unsigned)__builtin_amdgcn_readfirstlane(ddst)); glds16s(dsrc + TS, dvoff, (unsigned)__builtin_amdgcn_readfirstlane(ddst + TS)); }
;     WB(2);
;     FRAG(kf[0], LDS_K); FRAG(kf[1], LDS_K + 2048);
;     p0 = MFQK(kf[0]); p1 = MFQK(kf[1]);
; #pragma unroll
;     for (int r = 0; r < 16; ++r) p0[r] = EX(p0[r]);
; #pragma unroll
;     for (int r = 0; r < 4; ++r) p1[r] = EX(p1[r]);
; #pragma unroll
;     for (int w = 0; w < 3; ++w) pfA[w] = pk8(pfA[w], p0[4 * w], p0[4 * w + 1], p0[4 * w + 2], p0[4 * w + 3]);
;     WB(0);
;     DMA8(0, kw ? 3 : 2);
;     FRAG(kf[0], LDS_K + TS); FRAG(kf[1], LDS_K + TS + 2048);
;     WB(1);
;     for (int t = 1; t <= NT - 4; t += 4) {
.LBB0_438:
	s_waitcnt vmcnt(2) lgkmcnt(0)
	s_barrier
	ds_read_b128 v[2:5], v201
	ds_read_b128 v[6:9], v202
	ds_read_b128 v[34:37], v201 offset:2048
	ds_read_b128 v[38:41], v202 offset:2048
	s_lshr_b32 s8, s8, 6
	s_and_b64 s[14:15], s[14:15], exec
	s_cselect_b32 s30, s46, 0x2000
	s_waitcnt vmcnt(0) lgkmcnt(0)
	v_mfma_scale_f32_32x32x64_f8f6f4 v[2:17], v[2:9], v[132:139], v[18:33], v198, v197 op_sel_hi:[0,0,0]
	v_mov_b32_e32 v124, 0
	v_mov_b32_e32 v125, 0
	v_mov_b32_e32 v126, 0
	s_add_u32 s14, s67, s30
	s_addc_u32 s15, s66, 0
	s_add_i32 s30, s63, s30
	s_add_i32 s38, s40, s63
	s_add_i32 s39, s28, s63
	s_mov_b32 s40, -3
	s_nop 10
	v_exp_f32_e32 v1, v2
	v_mfma_scale_f32_32x32x64_f8f6f4 v[66:81], v[34:41], v[132:139], v[18:33], v198, v197 op_sel_hi:[0,0,0]
	v_exp_f32_e32 v2, v3
	v_exp_f32_e32 v3, v4
	v_exp_f32_e32 v4, v5
	v_exp_f32_e32 v5, v6
	v_exp_f32_e32 v6, v7
	v_exp_f32_e32 v7, v8
	v_exp_f32_e32 v8, v9
	v_exp_f32_e32 v9, v10
	v_exp_f32_e32 v10, v11
	s_waitcnt vmcnt(0) lgkmcnt(0)
	s_barrier
	v_exp_f32_e32 v11, v12
	v_exp_f32_e32 v12, v13
	v_cvt_pk_fp8_f32 v124, v1, v2
	v_cvt_pk_fp8_f32 v125, v5, v6
	v_cvt_pk_fp8_f32 v126, v9, v10
	s_mov_b32 s31, m0
	s_mov_b32 m0, s30
	s_nop 0
	global_load_lds_dwordx4 v164, s[14:15]
	s_mov_b32 m0, s31
	ds_read_b128 v[106:109], v201 offset:4096
	ds_read_b128 v[98:101], v201 offset:6144
	ds_read_b128 v[110:113], v202 offset:4096
	ds_read_b128 v[102:105], v202 offset:6144
	v_exp_f32_e32 v94, v14
	v_exp_f32_e32 v95, v15
	v_exp_f32_e32 v96, v16
	v_exp_f32_e32 v97, v17
	v_exp_f32_e32 v66, v66
	v_exp_f32_e32 v67, v67
	v_exp_f32_e32 v68, v68
	v_exp_f32_e32 v69, v69
	v_cvt_pk_fp8_f32 v124, v3, v4 op_sel:[0,0,1]
	v_cvt_pk_fp8_f32 v125, v7, v8 op_sel:[0,0,1]
	v_cvt_pk_fp8_f32 v126, v11, v12 op_sel:[0,0,1]
	s_waitcnt vmcnt(1) lgkmcnt(0)
	s_barrier
	s_add_i32 s31, s29, s63
	v_mov_b32_e32 v2, 0
	s_add_u32 s28, s14, 0x4000
	s_addc_u32 s29, s15, 0
	v_mov_b32_e32 v3, v2
	v_mov_b32_e32 v4, v2
	v_mov_b32_e32 v5, v2
	v_mov_b32_e32 v6, v2
	v_mov_b32_e32 v7, v2
	v_mov_b32_e32 v8, v2
	v_mov_b32_e32 v9, v2
	v_mov_b32_e32 v10, v2
	v_mov_b32_e32 v11, v2
	v_mov_b32_e32 v12, v2
	v_mov_b32_e32 v13, v2
	v_mov_b32_e32 v14, v2
	v_mov_b32_e32 v15, v2
	v_mov_b32_e32 v16, v2
	v_mov_b32_e32 v17, v2
	v_mov_b32_e32 v127, v2
	v_mov_b32_e32 v128, v2
	v_mov_b32_e32 v129, v2
	v_mov_b32_e32 v130, v2
	v_mov_b32_e32 v131, v2
	v_mov_b32_e32 v140, v2
	v_mov_b32_e32 v141, v2
	v_mov_b32_e32 v142, v2
	v_mov_b32_e32 v143, v2
	v_mov_b32_e32 v144, v2
	v_mov_b32_e32 v145, v2
	v_mov_b32_e32 v146, v2
	v_mov_b32_e32 v147, v2
	v_mov_b32_e32 v34, v2
	v_mov_b32_e32 v35, v2
	v_mov_b32_e32 v36, v2
	v_mov_b32_e32 v37, v2
	v_mov_b32_e32 v38, v2
	v_mov_b32_e32 v39, v2
	v_mov_b32_e32 v40, v2
	v_mov_b32_e32 v41, v2
	v_mov_b32_e32 v42, v2
	v_mov_b32_e32 v43, v2
	v_mov_b32_e32 v44, v2
	v_mov_b32_e32 v45, v2
	v_mov_b32_e32 v46, v2
	v_mov_b32_e32 v47, v2
	v_mov_b32_e32 v48, v2
	v_mov_b32_e32 v49, v2
	v_mov_b32_e32 v50, v2
	v_mov_b32_e32 v51, v2
	v_mov_b32_e32 v52, v2
	v_mov_b32_e32 v53, v2
	v_mov_b32_e32 v54, v2
	v_mov_b32_e32 v55, v2
	v_mov_b32_e32 v56, v2
	v_mov_b32_e32 v57, v2
	v_mov_b32_e32 v58, v2
	v_mov_b32_e32 v59, v2
	v_mov_b32_e32 v60, v2
	v_mov_b32_e32 v61, v2
	v_mov_b32_e32 v62, v2
	v_mov_b32_e32 v63, v2
	v_mov_b32_e32 v64, v2
	v_mov_b32_e32 v65, v2
	.p2align	6

; #define EX(v) __builtin_amdgcn_exp2f(v)
; __device__ __forceinline__ void attn_unit_d16(const UnitDesc& U, char* shm, float lam, const float* subw) {
;     ...
;     const int tid = threadIdx.x, lane = tid & 63, c16 = lane & 15, g = lane >> 4; const int wid = __builtin_amdgcn_readfirstlane(tid >> 6);
;     const unsigned lds0 = (unsigned)(uintptr_t)shm;
;     const int map = wid >> 2;
;     unsigned koff, voff; unsigned kdst[NPK], vdst[NPV];
;     { const int key = 8 * wid + (lane >> 3), pp = lane & 7;
;       koff = (unsigned)(key * U.KP + (pp ^ ((key >> 1) & 7)) * 8) * 2u; voff = (unsigned)(key * U.VP + ((((pp >> 1) ^ ((key >> 1) & 3)) << 1) + (pp & 1)) * 8) * 2u;
; #pragma unroll
;       for (int pc = 0; pc < NPK; ++pc) kdst[pc] = lds0 + LDS_K + pc * 8192 + wid * 1024;
; #pragma unroll
;       for (int pc = 0; pc < NPV; ++pc) vdst[pc] = lds0 + LDS_V + pc * 8192 + wid * 1024; }
;     ...
;     const lds_cptr shm3 = (lds_cptr)shm;
;     lds_cptr kpb[2];
; #pragma unroll
;     for (int ds = 0; ds < 2; ++ds) kpb[ds] = shm3 + LDS_K + map * 8192 + c16 * 128 + (((4 * ds + g) ^ (c16 >> 1)) << 4);
;     lds_cptr vpb[4];
;     { const int q4 = c16 >> 2, p = c16 & 3, ko = 4 * g + q4, swz = (ko >> 1) & 3;
; #pragma unroll
;       for (int b = 0; b < 4; ++b) vpb[b] = shm3 + LDS_V + ko * 128 + ((b ^ swz) << 5) + p * 8; }
;     bf16x8 qr[2][2];
; #pragma unroll
;     for (int qt = 0; qt < 2; ++qt)
; #pragma unroll
;         for (int ds = 0; ds < 2; ++ds) qr[qt][ds] = *reinterpret_cast<const bf16x8*>(U.Qw + (size_t)(16 * qt + c16) * 512 + 32 * ds + 8 * g);
;     ...
;     DMA_K(0, 0); DMA_V(0, 0); DMA_K(1, 1); DMA_K(2, 2); DMA_V(1, 1);
;     ATT_WAIT_BAR(8);
;     { const int kn_ = 0;
; #pragma unroll
;       for (int j = 0; j < 8; ++j) KRD16(j); }
; #pragma unroll
;     for (int kt = 0; kt < 4; ++kt)
; #pragma unroll
;         for (int qt = 0; qt < 2; ++qt) { S[kt][qt] = MF16(kf[kt][0], qr[qt][0], zero4); S[kt][qt] = MF16(kf[kt][1], qr[qt][1], S[kt][qt]); }
; #pragma unroll
;     for (int kt = 0; kt < 4; ++kt)
; #pragma unroll
;         for (int qt = 0; qt < 2; ++qt)
; #pragma unroll
;             for (int r = 0; r < 4; ++r) S[kt][qt][r] = EX(S[kt][qt][r]);
; #pragma unroll
;     for (int qt = 0; qt < 2; ++qt)
; #pragma unroll
;         for (int ks = 0; ks < 2; ++ks) { pa[qt][ks][0] = cvtpk_s(S[2 * ks][qt][0], S[2 * ks][qt][1]); pa[qt][ks][1] = cvtpk_s(S[2 * ks][qt][2], S[2 * ks][qt][3]);
.LBB0_443:
	s_mul_i32 s53, s53, 3
	s_ashr_i32 s68, s52, 1
	s_lshl_b32 s0, s12, 5
	s_add_i32 s8, s68, s53
	s_and_b32 s0, s0, 32
	s_ashr_i32 s10, s8, 2
	s_or_b32 s12, s0, s13
	s_ashr_i32 s11, s10, 31
	s_lshl_b32 s12, s12, 7
	s_lshl_b64 s[0:1], s[10:11], 13
	s_or_b32 s12, s12, s43
	s_or_b32 s0, s0, s12
	s_lshl_b64 s[12:13], s[0:1], 10
	s_add_u32 s12, s20, s12
	s_addc_u32 s13, s21, s13
	s_lshl_b32 s8, s8, 7
	s_and_b32 s8, s8, 0x180
	s_lshl_b32 s30, s8, 1
	s_add_u32 s12, s12, s30
	s_addc_u32 s13, s13, 0
	s_add_u32 s12, s12, s48
	s_addc_u32 s13, s13, 0
	v_mov_b32_e32 v187, v183
	v_lshl_add_u64 v[2:3], s[12:13], 0, v[186:187]
	v_mov_b32_e32 v189, v183
	v_lshl_add_u64 v[2:3], v[2:3], 0, v[188:189]
	global_load_dwordx4 v[10:13], v[2:3], off
	global_load_dwordx4 v[14:17], v[2:3], off offset:64
	v_add_co_u32_e32 v2, vcc, s45, v2
	s_lshl_b64 s[14:15], s[10:11], 23
	s_nop 0
	v_addc_co_u32_e32 v3, vcc, 0, v3, vcc
	global_load_dwordx4 v[18:21], v[2:3], off
	global_load_dwordx4 v[22:25], v[2:3], off offset:64
	s_add_u32 s10, s22, s14
	s_addc_u32 s11, s23, s15
	s_add_u32 s28, s10, s30
	s_addc_u32 s29, s11, 0
	s_add_u32 s10, s24, s14
	s_addc_u32 s11, s25, s15
	s_add_u32 s10, s10, s30
	v_readfirstlane_b32 s12, v180
	s_addc_u32 s11, s11, 0
	s_lshr_b32 s13, s12, 6
	v_lshl_or_b32 v1, s13, 3, v191
	s_lshl_b32 s30, s13, 10
	v_lshlrev_b32_e32 v2, 10, v1
	v_lshrrev_b32_e32 v1, 1, v1
	s_cmp_lg_u32 0, -1
	v_xor_b32_e32 v1, v1, v180
	s_cselect_b32 s31, 0, 0
	s_lshl_b32 s40, s12, 5
	v_lshlrev_b32_e32 v1, 4, v1
	s_add_i32 s30, s30, s31
	s_and_b32 s40, s40, 0x7fffe000
	s_waitcnt vmcnt(0)
	v_and_or_b32 v157, v1, s47, v2
	s_add_i32 s31, s30, 0x2000
	s_add_i32 s38, s30, 0x10000
	s_add_i32 s39, s30, 0x12000
	v_add_u32_e32 v6, s40, v194
	s_mov_b32 s40, m0
	s_mov_b32 m0, s30
	s_nop 0
	global_load_lds_dwordx4 v157, s[28:29]
	s_mov_b32 m0, s40
	s_add_u32 s40, s28, 0x80
	s_addc_u32 s41, s29, 0
	s_mov_b32 s52, m0
	s_mov_b32 m0, s31
	s_nop 0
	global_load_lds_dwordx4 v157, s[40:41]
	s_mov_b32 m0, s52
	v_or_b32_e32 v156, v2, v192
	s_mov_b32 s40, m0
	s_mov_b32 m0, s38
	s_nop 0
	global_load_lds_dwordx4 v156, s[10:11]
	s_mov_b32 m0, s40
	s_add_u32 s40, s10, 0x80
	s_addc_u32 s41, s11, 0
	s_mov_b32 s52, m0
	s_mov_b32 m0, s39
	s_nop 0
	global_load_lds_dwordx4 v156, s[40:41]
	s_mov_b32 m0, s52
	s_add_u32 s52, s28, 0x10000
	s_addc_u32 s53, s29, 0
	s_add_i32 s40, s30, 0x4000
	s_mov_b32 s41, m0
	s_mov_b32 m0, s40
	s_nop 0
	global_load_lds_dwordx4 v157, s[52:53]
	s_mov_b32 m0, s41
	s_add_u32 s52, s28, 0x10080
	s_addc_u32 s53, s29, 0
	s_add_i32 s41, s31, 0x4000
	s_mov_b32 s62, m0
	s_mov_b32 m0, s41
	s_nop 0
	global_load_lds_dwordx4 v157, s[52:53]
	s_mov_b32 m0, s62
	s_add_u32 s62, s28, 0x20000
	s_addc_u32 s63, s29, 0
	s_add_i32 s52, s30, 0x8000
	s_mov_b32 s53, m0
	s_mov_b32 m0, s52
	s_nop 0
	global_load_lds_dwordx4 v157, s[62:63]
	s_mov_b32 m0, s53
	s_add_u32 s62, s28, 0x20080
	s_addc_u32 s63, s29, 0
	s_add_i32 s53, s31, 0x8000
	s_mov_b32 s66, m0
	s_mov_b32 m0, s53
	s_nop 0
	global_load_lds_dwordx4 v157, s[62:63]
	s_mov_b32 m0, s66
	s_add_u32 s66, s10, 0x10000
	s_addc_u32 s67, s11, 0
	s_add_i32 s62, s38, 0x4000
	s_mov_b32 s63, m0
	s_mov_b32 m0, s62
	s_nop 0
	global_load_lds_dwordx4 v156, s[66:67]
	s_mov_b32 m0, s63
	s_add_u32 s66, s10, 0x10080
	s_addc_u32 s67, s11, 0
	s_add_i32 s63, s39, 0x4000
	s_mov_b32 s69, m0
	s_mov_b32 m0, s63
	s_nop 0
	global_load_lds_dwordx4 v156, s[66:67]
	s_mov_b32 m0, s69
	v_add_u32_e32 v1, v6, v195
	s_waitcnt vmcnt(8) lgkmcnt(0)
	s_barrier
	ds_read_b128 v[2:5], v1
	v_add_u32_e32 v115, v6, v196
	ds_read_b128 v[6:9], v1 offset:2048
	s_waitcnt lgkmcnt(1)
	v_mfma_f32_16x16x32_bf16 v[26:29], v[2:5], v[10:13], 0
	ds_read_b128 v[30:33], v115
	ds_read_b128 v[34:37], v115 offset:2048
	s_add_u32 s74, s28, 0x30000
	s_addc_u32 s75, s29, 0
	v_mfma_f32_16x16x32_bf16 v[2:5], v[2:5], v[18:21], 0
	s_add_i32 s66, s30, 0xc000
	s_waitcnt lgkmcnt(1)
	v_mfma_f32_16x16x32_bf16 v[26:29], v[30:33], v[14:17], v[26:29]
	v_mfma_f32_16x16x32_bf16 v[2:5], v[30:33], v[22:25], v[2:5]
	v_mfma_f32_16x16x32_bf16 v[30:33], v[6:9], v[10:13], 0
	s_nop 5
	v_exp_f32_e32 v26, v26
	v_exp_f32_e32 v27, v27
	v_exp_f32_e32 v28, v28
	v_mfma_f32_16x16x32_bf16 v[6:9], v[6:9], v[18:21], 0
	v_exp_f32_e32 v29, v29
	v_exp_f32_e32 v2, v2
	v_exp_f32_e32 v3, v3
	s_waitcnt lgkmcnt(0)
	v_mfma_f32_16x16x32_bf16 v[30:33], v[34:37], v[14:17], v[30:33]
	v_exp_f32_e32 v4, v4
	v_exp_f32_e32 v5, v5
	v_cvt_pk_bf16_f32 v2, v2, v3
	v_mfma_f32_16x16x32_bf16 v[6:9], v[34:37], v[22:25], v[6:9]
	ds_read_b128 v[34:37], v1 offset:4096
	ds_read_b128 v[38:41], v1 offset:6144
	ds_read_b128 v[46:49], v115 offset:4096
	ds_read_b128 v[50:53], v115 offset:6144
	s_waitcnt vmcnt(0) lgkmcnt(0)
	s_barrier
; #define ATT_WAIT_BAR(N) asm volatile("s_waitcnt vmcnt(" #N ") lgkmcnt(0)\n\ts_barrier" ::: "memory")
; #define DMA_K(t, slot) do { _Pragma("unroll") for (int pc_ = 0; pc_ < NPK; ++pc_) glds16s(U.Kt + (size_t)(t) * 64 * U.KP + pc_ * 64, koff, (unsigned)__builtin_amdgcn_readfirstlane(kdst[pc_] + (slot) * KS)); } while (0)
; #define DMA_V(t, slot) do { _Pragma("unroll") for (int pc_ = 0; pc_ < NPV; ++pc_) glds16s(U.Vt + (size_t)(t) * 64 * U.VP + pc_ * 64, voff, (unsigned)__builtin_amdgcn_readfirstlane(vdst[pc_] + (slot) * VS)); } while (0)
; #define DMA_K(t, slot) do { _Pragma("unroll") for (int pc_ = 0; pc_ < NPK; ++pc_) glds16s(U.Kt + (size_t)(t) * 64 * U.KP + pc_ * 64, koff, (unsigned)__builtin_amdgcn_readfirstlane(kdst[pc_] + (slot) * KS)); } while (0)
; #define DMA_V(t, slot) do { _Pragma("unroll") for (int pc_ = 0; pc_ < NPV; ++pc_) glds16s(U.Vt + (size_t)(t) * 64 * U.VP + pc_ * 64, voff, (unsigned)__builtin_amdgcn_readfirstlane(vdst[pc_] + (slot) * VS)); } while (0)
; #define KRD16(j) do { kf[(j) >> 1][(j) & 1] = *(const __attribute__((address_space(3))) bf16x8*)(kpb[(j) & 1] + kn_ + ((j) >> 1) * 2048); } while (0)
; __device__ __forceinline__ void attn_unit_d16(const UnitDesc& U, char* shm, float lam, const float* subw) {
;     ...
;     for (int qt = 0; qt < 2; ++qt) { ls[qt] = zero4;
; #pragma unroll
;         for (int dt = 0; dt < 8; ++dt) o[qt][dt] = zero4; }
;     ...
;     DMA_K(3, 3); DMA_V(VAH, 2);
;     { const int kn_ = KS;
; #pragma unroll
;       for (int j = 0; j < 8; ++j) KRD16(j); }
;     ATT_WAIT_BAR(4);
	s_waitcnt lgkmcnt(3)
	v_mfma_f32_16x16x32_bf16 v[42:45], v[34:37], v[10:13], 0
	s_mov_b32 s67, m0
	s_mov_b32 m0, s66
	s_nop 0
	global_load_lds_dwordx4 v157, s[74:75]
	s_mov_b32 m0, s67
	s_add_u32 s74, s28, 0x30080
	s_addc_u32 s75, s29, 0
	v_mfma_f32_16x16x32_bf16 v[34:37], v[34:37], v[18:21], 0
	s_add_i32 s28, s31, 0xc000
	s_mov_b32 s29, m0
	s_mov_b32 m0, s28
	s_nop 0
	global_load_lds_dwordx4 v157, s[74:75]
	s_mov_b32 m0, s29
	s_add_u32 s74, s10, 0x20000
	s_waitcnt lgkmcnt(1)
	v_mfma_f32_16x16x32_bf16 v[42:45], v[46:49], v[14:17], v[42:45]
	s_addc_u32 s75, s11, 0
	s_add_i32 s29, s38, 0x8000
	s_mov_b32 s67, m0
	s_mov_b32 m0, s29
	s_nop 0
	global_load_lds_dwordx4 v156, s[74:75]
	s_mov_b32 m0, s67
	v_mfma_f32_16x16x32_bf16 v[34:37], v[46:49], v[22:25], v[34:37]
	s_add_u32 s74, s10, 0x20080
	s_addc_u32 s75, s11, 0
	s_add_i32 s67, s39, 0x8000
	v_mfma_f32_16x16x32_bf16 v[46:49], v[38:41], v[10:13], 0
	s_mov_b32 s69, m0
	s_mov_b32 m0, s67
	s_nop 0
	global_load_lds_dwordx4 v156, s[74:75]
	s_mov_b32 m0, s69
	s_lshl_b32 s68, s68, 7
	s_lshl_b32 s33, s33, 7
	v_mfma_f32_16x16x32_bf16 v[38:41], v[38:41], v[18:21], 0
	v_exp_f32_e32 v32, v32
	v_exp_f32_e32 v33, v33
	s_sub_i32 s33, s68, s33
	s_waitcnt lgkmcnt(0)
	v_mfma_f32_16x16x32_bf16 v[46:49], v[50:53], v[14:17], v[46:49]
	v_exp_f32_e32 v30, v30
	v_exp_f32_e32 v31, v31
	v_exp_f32_e32 v42, v42
	v_mfma_f32_16x16x32_bf16 v[38:41], v[50:53], v[22:25], v[38:41]
	v_exp_f32_e32 v50, v6
	v_exp_f32_e32 v51, v7
	v_cvt_pk_bf16_f32 v6, v26, v27
	v_cvt_pk_bf16_f32 v7, v28, v29
	ds_read_b128 v[110:113], v1 offset:16384
	ds_read_b128 v[116:119], v1 offset:18432
	ds_read_b128 v[26:29], v115 offset:16384
	ds_read_b128 v[120:123], v115 offset:18432
	ds_read_b128 v[124:127], v1 offset:20480
	ds_read_b128 v[128:131], v1 offset:22528
	ds_read_b128 v[132:135], v115 offset:20480
	ds_read_b128 v[136:139], v115 offset:22528
	v_exp_f32_e32 v38, v38
	v_exp_f32_e32 v39, v39
	v_exp_f32_e32 v52, v8
	v_exp_f32_e32 v53, v9
	v_exp_f32_e32 v43, v43
	v_exp_f32_e32 v44, v44
	v_exp_f32_e32 v45, v45
	v_exp_f32_e32 v54, v34
	v_exp_f32_e32 v55, v35
	v_exp_f32_e32 v56, v36
	v_exp_f32_e32 v57, v37
	v_exp_f32_e32 v36, v46
	v_exp_f32_e32 v37, v47
	v_exp_f32_e32 v46, v48
	v_exp_f32_e32 v47, v49
	v_exp_f32_e32 v40, v40
	v_exp_f32_e32 v41, v41
	s_lshl_b32 s33, s33, 1
	s_and_b32 s33, s33, 0x300
	s_waitcnt vmcnt(4) lgkmcnt(0)
	s_barrier
	s_or_b32 s14, s14, s33
	v_cvt_pk_bf16_f32 v9, v32, v33
	v_cvt_pk_bf16_f32 v32, v38, v39
	s_add_u32 s14, s3, s14
	v_mov_b32_e32 v38, 0
	v_cvt_pk_bf16_f32 v8, v30, v31
	v_cvt_pk_bf16_f32 v34, v42, v43
	v_cvt_pk_bf16_f32 v35, v44, v45
	v_cvt_pk_bf16_f32 v36, v36, v37
	v_cvt_pk_bf16_f32 v37, v46, v47
	v_cvt_pk_bf16_f32 v3, v4, v5
	v_cvt_pk_bf16_f32 v4, v50, v51
	v_cvt_pk_bf16_f32 v5, v52, v53
	v_cvt_pk_bf16_f32 v30, v54, v55
	v_cvt_pk_bf16_f32 v31, v56, v57
	v_cvt_pk_bf16_f32 v33, v40, v41
	s_addc_u32 s15, s44, s15
	s_mov_b32 s33, -3
	v_mov_b32_e32 v39, v38
	v_mov_b32_e32 v40, v38
	v_mov_b32_e32 v41, v38
	v_mov_b32_e32 v42, v38
	v_mov_b32_e32 v43, v38
	v_mov_b32_e32 v44, v38
	v_mov_b32_e32 v45, v38
	v_mov_b32_e32 v50, v38
	v_mov_b32_e32 v51, v38
	v_mov_b32_e32 v52, v38
	v_mov_b32_e32 v53, v38
	v_mov_b32_e32 v58, v38
	v_mov_b32_e32 v59, v38
	v_mov_b32_e32 v60, v38
	v_mov_b32_e32 v61, v38
	v_mov_b32_e32 v66, v38
	v_mov_b32_e32 v67, v38
	v_mov_b32_e32 v68, v38
	v_mov_b32_e32 v69, v38
	v_mov_b32_e32 v74, v38
	v_mov_b32_e32 v75, v38
	v_mov_b32_e32 v76, v38
	v_mov_b32_e32 v77, v38
	v_mov_b32_e32 v82, v38
	v_mov_b32_e32 v83, v38
	v_mov_b32_e32 v84, v38
	v_mov_b32_e32 v85, v38
	v_mov_b32_e32 v90, v38
	v_mov_b32_e32 v91, v38
	v_mov_b32_e32 v92, v38
	v_mov_b32_e32 v93, v38
	v_mov_b32_e32 v46, v38
	v_mov_b32_e32 v47, v38
	v_mov_b32_e32 v48, v38
	v_mov_b32_e32 v49, v38
	v_mov_b32_e32 v54, v38
	v_mov_b32_e32 v55, v38
	v_mov_b32_e32 v56, v38
	v_mov_b32_e32 v57, v38
	v_mov_b32_e32 v62, v38
	v_mov_b32_e32 v63, v38
	v_mov_b32_e32 v64, v38
	v_mov_b32_e32 v65, v38
	v_mov_b32_e32 v70, v38
	v_mov_b32_e32 v71, v38
	v_mov_b32_e32 v72, v38
	v_mov_b32_e32 v73, v38
	v_mov_b32_e32 v78, v38
	v_mov_b32_e32 v79, v38
	v_mov_b32_e32 v80, v38
	v_mov_b32_e32 v81, v38
	v_mov_b32_e32 v86, v38
	v_mov_b32_e32 v87, v38
	v_mov_b32_e32 v88, v38
	v_mov_b32_e32 v89, v38
	v_mov_b32_e32 v94, v38
	v_mov_b32_e32 v95, v38
	v_mov_b32_e32 v96, v38
	v_mov_b32_e32 v97, v38
	v_mov_b32_e32 v98, v38
	v_mov_b32_e32 v99, v38
	v_mov_b32_e32 v100, v38
	v_mov_b32_e32 v101, v38
	v_mov_b32_e32 v102, v38
	v_mov_b32_e32 v103, v38
	v_mov_b32_e32 v104, v38
	v_mov_b32_e32 v105, v38
	v_mov_b32_e32 v106, v38
	v_mov_b32_e32 v107, v38
	v_mov_b32_e32 v108, v38
	v_mov_b32_e32 v109, v38
	.p2align	6

;     __host__ __device__ bool next(int i, Unit& o) const { if (i != 0) return false; o = u; return true; }
; template <class Epi, class Sched, bool ALIGN_EPI = false, bool SP2 = false>
; __device__ __forceinline__ void gemm_phase(PG8_LAS unsigned char* lds, const Gemm g, const Sched& S, const Epi& E) {
;     ...
;         const bool has_next = S.next(ui + 1, nxt);
;         const char* nA = has_next ? (const char*)g.A + (size_t)nxt.pm * tstep : cA; const char* nB = has_next ? (const char*)g.Bt + (size_t)nxt.pn * tstep : cB;
;         for (int t = 0; t < nt; t += 2) {
;             const bool last = (t == nt - 2);
;             const char* a1 = cA + (size_t)(t + 1) * kstep;
;             const char* a2 = last ? nA : cA + (size_t)(t + 2) * kstep; const char* b2 = last ? nB : cB + (size_t)(t + 2) * kstep;
;             const char* a3 = a2 + kstep; const char* b3 = b2 + kstep;
;     ...
; #pragma unroll
;         for (int a = 0; a < 2; ++a)
; #pragma unroll
;             for (int b = 0; b < 2; ++b)
; #pragma unroll
;                 for (int m = 0; m < 4; ++m)
; #pragma unroll
;                     for (int n = 0; n < 2; ++n) acc[a][b][m][n] = (f32x4){0.f, 0.f, 0.f, 0.f};
;         cur = nxt; cA = nA; cB = nB; ++ui;
.LBB0_512:
	s_ashr_i32 s15, s14, 31
	s_lshl_b64 s[22:23], s[14:15], 19
	s_add_u32 s22, s94, s22
	s_addc_u32 s23, s95, s23
	s_and_b64 s[24:25], s[0:1], exec
	s_cselect_b32 s15, s23, s29
	s_cselect_b32 s49, s22, s28
	s_ashr_i32 s11, s10, 31
	s_lshl_b64 s[24:25], s[10:11], 19
	v_readlane_b32 s36, v252, 7
	v_readlane_b32 s37, v252, 8
	s_add_u32 s24, s36, s24
	s_addc_u32 s25, s37, s25
	s_and_b64 s[36:37], s[0:1], exec
	s_cselect_b32 s11, s25, s31
	s_cselect_b32 s50, s24, s30
	s_add_u32 s28, s28, 0x40080
	s_addc_u32 s29, s29, 0
	s_add_u32 s51, s30, 0x100
	v_mov_b32_e32 v0, 0
	s_addc_u32 s52, s31, 0
	s_mov_b32 s53, -2
	v_mov_b32_e32 v1, v0
	v_mov_b32_e32 v2, v0
	v_mov_b32_e32 v3, v0
	v_mov_b32_e32 v4, v0
	v_mov_b32_e32 v5, v0
	v_mov_b32_e32 v6, v0
	v_mov_b32_e32 v7, v0
	v_mov_b32_e32 v16, v0
	v_mov_b32_e32 v17, v0
	v_mov_b32_e32 v18, v0
	v_mov_b32_e32 v19, v0
	v_mov_b32_e32 v20, v0
	v_mov_b32_e32 v21, v0
	v_mov_b32_e32 v22, v0
	v_mov_b32_e32 v23, v0
	v_mov_b32_e32 v32, v0
	v_mov_b32_e32 v33, v0
	v_mov_b32_e32 v34, v0
	v_mov_b32_e32 v35, v0
	v_mov_b32_e32 v36, v0
	v_mov_b32_e32 v37, v0
	v_mov_b32_e32 v38, v0
	v_mov_b32_e32 v39, v0
	v_mov_b32_e32 v48, v0
	v_mov_b32_e32 v49, v0
	v_mov_b32_e32 v50, v0
	v_mov_b32_e32 v51, v0
	v_mov_b32_e32 v52, v0
	v_mov_b32_e32 v53, v0
	v_mov_b32_e32 v54, v0
	v_mov_b32_e32 v55, v0
	v_mov_b32_e32 v8, v0
	v_mov_b32_e32 v9, v0
	v_mov_b32_e32 v10, v0
	v_mov_b32_e32 v11, v0
	v_mov_b32_e32 v12, v0
	v_mov_b32_e32 v13, v0
	v_mov_b32_e32 v14, v0
	v_mov_b32_e32 v15, v0
	v_mov_b32_e32 v24, v0
	v_mov_b32_e32 v25, v0
	v_mov_b32_e32 v26, v0
	v_mov_b32_e32 v27, v0
	v_mov_b32_e32 v28, v0
	v_mov_b32_e32 v29, v0
	v_mov_b32_e32 v30, v0
	v_mov_b32_e32 v31, v0
	v_mov_b32_e32 v40, v0
	v_mov_b32_e32 v41, v0
	v_mov_b32_e32 v42, v0
	v_mov_b32_e32 v43, v0
	v_mov_b32_e32 v44, v0
	v_mov_b32_e32 v45, v0
	v_mov_b32_e32 v46, v0
	v_mov_b32_e32 v47, v0
	v_mov_b32_e32 v56, v0
	v_mov_b32_e32 v57, v0
	v_mov_b32_e32 v58, v0
	v_mov_b32_e32 v59, v0
	v_mov_b32_e32 v60, v0
	v_mov_b32_e32 v61, v0
	v_mov_b32_e32 v62, v0
	v_mov_b32_e32 v63, v0
	v_mov_b32_e32 v64, v0
	v_mov_b32_e32 v65, v0
	v_mov_b32_e32 v66, v0
	v_mov_b32_e32 v67, v0
	v_mov_b32_e32 v68, v0
	v_mov_b32_e32 v69, v0
	v_mov_b32_e32 v70, v0
	v_mov_b32_e32 v71, v0
	v_mov_b32_e32 v80, v0
	v_mov_b32_e32 v81, v0
	v_mov_b32_e32 v82, v0
	v_mov_b32_e32 v83, v0
	v_mov_b32_e32 v84, v0
	v_mov_b32_e32 v85, v0
	v_mov_b32_e32 v86, v0
	v_mov_b32_e32 v87, v0
	v_mov_b32_e32 v96, v0
	v_mov_b32_e32 v97, v0
	v_mov_b32_e32 v98, v0
	v_mov_b32_e32 v99, v0
	v_mov_b32_e32 v100, v0
	v_mov_b32_e32 v101, v0
	v_mov_b32_e32 v102, v0
	v_mov_b32_e32 v103, v0
	v_mov_b32_e32 v112, v0
	v_mov_b32_e32 v113, v0
	v_mov_b32_e32 v114, v0
	v_mov_b32_e32 v115, v0
	v_mov_b32_e32 v116, v0
	v_mov_b32_e32 v117, v0
	v_mov_b32_e32 v118, v0
	v_mov_b32_e32 v119, v0
	v_mov_b32_e32 v72, v0
	v_mov_b32_e32 v73, v0
	v_mov_b32_e32 v74, v0
	v_mov_b32_e32 v75, v0
	v_mov_b32_e32 v76, v0
	v_mov_b32_e32 v77, v0
	v_mov_b32_e32 v78, v0
	v_mov_b32_e32 v79, v0
	v_mov_b32_e32 v88, v0
	v_mov_b32_e32 v89, v0
	v_mov_b32_e32 v90, v0
	v_mov_b32_e32 v91, v0
	v_mov_b32_e32 v92, v0
	v_mov_b32_e32 v93, v0
	v_mov_b32_e32 v94, v0
	v_mov_b32_e32 v95, v0
	v_mov_b32_e32 v104, v0
	v_mov_b32_e32 v105, v0
	v_mov_b32_e32 v106, v0
	v_mov_b32_e32 v107, v0
	v_mov_b32_e32 v108, v0
	v_mov_b32_e32 v109, v0
	v_mov_b32_e32 v110, v0
	v_mov_b32_e32 v111, v0
	v_mov_b32_e32 v120, v0
	v_mov_b32_e32 v121, v0
	v_mov_b32_e32 v122, v0
	v_mov_b32_e32 v123, v0
	v_mov_b32_e32 v124, v0
	v_mov_b32_e32 v125, v0
	v_mov_b32_e32 v126, v0
	v_mov_b32_e32 v127, v0
	.p2align	6

; #define PG8_STAGE(bufoff, gbase, voff) do { _Pragma("unroll") for (int _i = 0; _i < 2; ++_i) \
;         __builtin_amdgcn_global_load_lds((const unsigned*)((const char*)(gbase) + (voff)[_i]), (PG8_LAS unsigned*)(lds + (bufoff) + ldsw + _i * 8192), 16, 0, 0); } while (0)
; #define PG8_WAIT_V(n) asm volatile("s_waitcnt vmcnt(" #n ")" ::: "memory")
; #define PG8_BAR __builtin_amdgcn_s_barrier()
; template <class Epi, class Sched, bool ALIGN_EPI = false, bool SP2 = false>
; __device__ __forceinline__ void gemm_phase(PG8_LAS unsigned char* lds, const Gemm g, const Sched& S, const Epi& E) {
;     ...
; #pragma unroll
;     for (int a = 0; a < 2; ++a)
; #pragma unroll
;         for (int b = 0; b < 2; ++b)
; #pragma unroll
;             for (int m = 0; m < 4; ++m)
; #pragma unroll
;                 for (int n = 0; n < 2; ++n) acc[a][b][m][n] = (f32x4){0.f, 0.f, 0.f, 0.f};
;     ...
;         PG8_STAGE(PG8_SB(0, 0), cB, voffB); PG8_STAGE(PG8_SB(0, 1), cB + hstep, voffB); PG8_STAGE(PG8_SA(0, 0), cA, voffA); PG8_STAGE(PG8_SA(0, 1), cA + hstep, voffA);
;         if (wr == 1) PG8_BAR;
;         PG8_WAIT_V(2); PG8_BAR;
;         PG8_STAGE(PG8_SB(1, 0), cB + kstep, voffB); PG8_STAGE(PG8_SA(1, 0), cA + kstep, voffA); PG8_STAGE(PG8_SB(1, 1), cB + hstep + kstep, voffB);
;         PG8_WAIT_V(6); PG8_BAR;
.LBB0_585:
	s_lshl_b32 s24, s24, 5
	s_add_i32 m0, s16, 0x18000
	v_lshl_add_u64 v[0:1], v[0:1], 0, s[14:15]
	s_and_b32 s42, s24, 0x60
	s_waitcnt vmcnt(2)
	s_barrier
	global_load_lds_dwordx4 v[0:1], off
	v_lshl_add_u64 v[0:1], v[2:3], 0, s[14:15]
	s_add_i32 m0, s16, 0x1a000
	s_add_i32 s46, s16, 0x8000
	s_add_i32 s47, s16, 0xa000
	global_load_lds_dwordx4 v[0:1], off
	v_lshl_add_u64 v[0:1], v[6:7], 0, s[14:15]
	s_mov_b32 m0, s46
	s_add_u32 s24, s0, 0x40080
	global_load_lds_dwordx4 v[0:1], off
	v_lshl_add_u64 v[0:1], v[4:5], 0, s[14:15]
	s_mov_b32 m0, s47
	s_addc_u32 s25, s1, 0
	global_load_lds_dwordx4 v[0:1], off
	s_add_i32 m0, s16, 0x1c000
	v_lshl_add_u64 v[0:1], s[24:25], 0, v[128:129]
	global_load_lds_dwordx4 v[0:1], off
	v_lshl_add_u64 v[0:1], s[24:25], 0, v[130:131]
	s_add_i32 m0, s16, 0x1e000
	s_add_u32 s48, s58, s22
	global_load_lds_dwordx4 v[0:1], off
	s_waitcnt vmcnt(6)
	s_addc_u32 s49, s59, s23
	v_lshl_or_b32 v8, s12, 13, v144
	s_add_u32 s50, s28, s18
	v_mov_b32_e32 v0, 0
	v_lshl_or_b32 v159, s42, 7, v145
	v_lshl_add_u64 v[140:141], v[132:133], 0, s[22:23]
	v_lshl_add_u64 v[142:143], v[134:135], 0, s[22:23]
	s_addc_u32 s51, s29, s19
	s_mov_b32 s52, -2
	s_mov_b64 s[18:19], 0
	v_add_u32_e32 v160, 0, v8
	v_mov_b32_e32 v1, v0
	v_mov_b32_e32 v2, v0
	v_mov_b32_e32 v3, v0
	v_mov_b32_e32 v4, v0
	v_mov_b32_e32 v5, v0
	v_mov_b32_e32 v6, v0
	v_mov_b32_e32 v7, v0
	v_mov_b32_e32 v8, v0
	v_mov_b32_e32 v9, v0
	v_mov_b32_e32 v10, v0
	v_mov_b32_e32 v11, v0
	v_mov_b32_e32 v12, v0
	v_mov_b32_e32 v13, v0
	v_mov_b32_e32 v14, v0
	v_mov_b32_e32 v15, v0
	v_mov_b32_e32 v24, v0
	v_mov_b32_e32 v25, v0
	v_mov_b32_e32 v26, v0
	v_mov_b32_e32 v27, v0
	v_mov_b32_e32 v28, v0
	v_mov_b32_e32 v29, v0
	v_mov_b32_e32 v30, v0
	v_mov_b32_e32 v31, v0
	v_mov_b32_e32 v40, v0
	v_mov_b32_e32 v41, v0
	v_mov_b32_e32 v42, v0
	v_mov_b32_e32 v43, v0
	v_mov_b32_e32 v48, v0
	v_mov_b32_e32 v49, v0
	v_mov_b32_e32 v50, v0
	v_mov_b32_e32 v51, v0
	v_mov_b32_e32 v16, v0
	v_mov_b32_e32 v17, v0
	v_mov_b32_e32 v18, v0
	v_mov_b32_e32 v19, v0
	v_mov_b32_e32 v20, v0
	v_mov_b32_e32 v21, v0
	v_mov_b32_e32 v22, v0
	v_mov_b32_e32 v23, v0
	v_mov_b32_e32 v32, v0
	v_mov_b32_e32 v33, v0
	v_mov_b32_e32 v34, v0
	v_mov_b32_e32 v35, v0
	v_mov_b32_e32 v36, v0
	v_mov_b32_e32 v37, v0
	v_mov_b32_e32 v38, v0
	v_mov_b32_e32 v39, v0
	v_mov_b32_e32 v44, v0
	v_mov_b32_e32 v45, v0
	v_mov_b32_e32 v46, v0
	v_mov_b32_e32 v47, v0
	v_mov_b32_e32 v52, v0
	v_mov_b32_e32 v53, v0
	v_mov_b32_e32 v54, v0
	v_mov_b32_e32 v55, v0
	v_mov_b32_e32 v56, v0
	v_mov_b32_e32 v57, v0
	v_mov_b32_e32 v58, v0
	v_mov_b32_e32 v59, v0
	v_mov_b32_e32 v60, v0
	v_mov_b32_e32 v61, v0
	v_mov_b32_e32 v62, v0
	v_mov_b32_e32 v63, v0
	v_mov_b32_e32 v64, v0
	v_mov_b32_e32 v65, v0
	v_mov_b32_e32 v66, v0
	v_mov_b32_e32 v67, v0
	v_mov_b32_e32 v68, v0
	v_mov_b32_e32 v69, v0
	v_mov_b32_e32 v70, v0
	v_mov_b32_e32 v71, v0
	v_mov_b32_e32 v72, v0
	v_mov_b32_e32 v73, v0
	v_mov_b32_e32 v74, v0
	v_mov_b32_e32 v75, v0
	v_mov_b32_e32 v80, v0
	v_mov_b32_e32 v81, v0
	v_mov_b32_e32 v82, v0
	v_mov_b32_e32 v83, v0
	v_mov_b32_e32 v88, v0
	v_mov_b32_e32 v89, v0
	v_mov_b32_e32 v90, v0
	v_mov_b32_e32 v91, v0
	v_mov_b32_e32 v96, v0
	v_mov_b32_e32 v97, v0
	v_mov_b32_e32 v98, v0
	v_mov_b32_e32 v99, v0
	v_mov_b32_e32 v104, v0
	v_mov_b32_e32 v105, v0
	v_mov_b32_e32 v106, v0
	v_mov_b32_e32 v107, v0
	v_mov_b32_e32 v116, v0
	v_mov_b32_e32 v117, v0
	v_mov_b32_e32 v118, v0
	v_mov_b32_e32 v119, v0
	v_mov_b32_e32 v76, v0
	v_mov_b32_e32 v77, v0
	v_mov_b32_e32 v78, v0
	v_mov_b32_e32 v79, v0
	v_mov_b32_e32 v84, v0
	v_mov_b32_e32 v85, v0
	v_mov_b32_e32 v86, v0
	v_mov_b32_e32 v87, v0
	v_mov_b32_e32 v92, v0
	v_mov_b32_e32 v93, v0
	v_mov_b32_e32 v94, v0
	v_mov_b32_e32 v95, v0
	v_mov_b32_e32 v100, v0
	v_mov_b32_e32 v101, v0
	v_mov_b32_e32 v102, v0
	v_mov_b32_e32 v103, v0
	v_mov_b32_e32 v108, v0
	v_mov_b32_e32 v109, v0
	v_mov_b32_e32 v110, v0
	v_mov_b32_e32 v111, v0
	v_mov_b32_e32 v112, v0
	v_mov_b32_e32 v113, v0
	v_mov_b32_e32 v114, v0
	v_mov_b32_e32 v115, v0
	v_mov_b32_e32 v120, v0
	v_mov_b32_e32 v121, v0
	v_mov_b32_e32 v122, v0
	v_mov_b32_e32 v123, v0
	v_mov_b32_e32 v124, v0
	v_mov_b32_e32 v125, v0
	v_mov_b32_e32 v126, v0
	v_mov_b32_e32 v127, v0
	s_barrier
	.p2align	6

; #define LAS __attribute__((address_space(3)))
; #define PB_RECS(rv, t, q) do { rv = *(const LAS recv_t*)(L + PW_REC + (t) * 512 + (g16 + NPB * (q)) * 4); } while (0)
; #define PB_LOADU(buf, T8, rv, soff) do { _Pragma("unroll") for (int i_ = 0; i_ < 4; ++i_) { \
;       int oa_; asm("v_mad_u32_u16 %0, %1, %2, %3" : "=v"(oa_) : "v"(rv[i_]), "s"(128), "v"(lo16)); \
;       buf[i_] = __builtin_bit_cast(v4u, __builtin_amdgcn_raw_buffer_load_b128(T8, oa_, soff, 0)); } } while (0)
; __device__ __forceinline__ void peer_block(int tok0, float* X1, const unsigned short* X1B, const int* TKI, const float* TKS, __amdgpu_buffer_rsrc_t U8r, __amdgpu_buffer_rsrc_t V6, const float* USC, const float* VSC,
;                                            const float* finw, pw_ptr L, int lane) {
;     ...
;         v4u bu[NBU][4]; v4u xq;
; #pragma unroll
;         for (int q = 0; q < NBU - 1; ++q) { PB_RECS(rv, 0, q); PB_LOADU(bu[q], U8r, rv, 0); }
;         for (int it = 0; it < NSU * PT; ++it) {
;             const int c = it / PT, t = it - c * PT; const int soff = c * SLU;
;             const int itn = it + 1, cn = itn / PT, tn = itn - cn * PT;
;             int rq[4];
;             xq = *(const LAS v4u*)(L + PW_Y + t * 1024 + 128 * c + 16 * m);
.LBB0_691:
	s_or_b64 exec, exec, s[40:41]
	v_add_u32_e32 v44, s33, v91
	ds_read_b128 v[0:3], v44
	s_waitcnt lgkmcnt(0)
	v_mad_u32_u16 v0, v0, s48, v90
	v_mad_u32_u16 v1, v1, s48, v90
	v_mad_u32_u16 v2, v2, s48, v90
	v_mad_u32_u16 v3, v3, s48, v90
	buffer_load_dwordx4 v[12:15], v0, s[60:63], 0 offen
	buffer_load_dwordx4 v[8:11], v1, s[60:63], 0 offen
	buffer_load_dwordx4 v[4:7], v2, s[60:63], 0 offen
	s_nop 0
	buffer_load_dwordx4 v[0:3], v3, s[60:63], 0 offen
	s_mov_b32 s10, 0
	s_mov_b32 s11, 1
	s_mov_b32 s40, 0
	s_mov_b32 s41, 0
	.p2align	6

; #define LAS __attribute__((address_space(3)))
; #define PB_RECS(rv, t, q) do { rv = *(const LAS recv_t*)(L + PW_REC + (t) * 512 + (g16 + NPB * (q)) * 4); } while (0)
; __device__ __forceinline__ h2g hswap_add32(h2g a, h2g b) { auto r = __builtin_amdgcn_permlane32_swap(__builtin_bit_cast(unsigned, a), __builtin_bit_cast(unsigned, b), false, false); return __builtin_bit_cast(h2g, (unsigned)r[0]) + __builtin_bit_cast(h2g, (unsigned)r[1]); }
; __device__ __forceinline__ void peer_block(int tok0, float* X1, const unsigned short* X1B, const int* TKI, const float* TKS, __amdgpu_buffer_rsrc_t U8r, __amdgpu_buffer_rsrc_t V6, const float* USC, const float* VSC,
;                                            const float* finw, pw_ptr L, int lane) {
;     ...
;         for (int it = 0; it < 4 * PT; ++it) {
;             const int c = it / PT, t = it - c * PT; const int soff = c * SLB;
;             const int itn = it + 1, cn = itn / PT, tn = itn - cn * PT;
;             h2g acc[16];
; #pragma unroll
;             for (int q = 0; q < NQ; ++q) {
;                 const int qa = q + NB - 1;
;                 if (qa < NQ) { PB_RECS(rv, t, qa); PB_LOAD(bb[qa % NB], V6, rv, soff); }
;                 else if (itn < 4 * PT) { PB_RECS(rv, tn, qa - NQ); PB_LOAD(bb[qa % NB], V6, rv, cn * SLB); }
;                 wv_t rw = *(const LAS wv_t*)(L + PW_ACT + t * 512 + (g16 + NPB * q) * 4); if (q == 0) pb_v_part<true>(bb[q % NB], rw, acc); else pb_v_part<false>(bb[q % NB], rw, acc);
;             }
;             h2g q8[8], q4[4], o2[2];
; #pragma unroll
;             for (int k = 0; k < 8; ++k) q8[k] = hswap_add32(acc[k], acc[k + 8]);
; #pragma unroll
;             for (int j = 0; j < 4; ++j) q4[j] = hswap_add16(q8[j], q8[j + 4]);
; #pragma unroll
;             for (int i = 0; i < 2; ++i) { const h2g keep = up ? q4[i + 2] : q4[i], send = up ? q4[i] : q4[i + 2];
;                 o2[i] = keep + __builtin_bit_cast(h2g, (unsigned)__builtin_amdgcn_update_dpp(0, (int)__builtin_bit_cast(unsigned, send), 0x128, 0xF, 0xF, true)); }
;             *(LAS v2u*)(L + PW_Y + t * 2048 + (256 * c + 32 * m + 4 * g) * 2) = (v2u){__builtin_bit_cast(unsigned, o2[0]), __builtin_bit_cast(unsigned, o2[1])};
;         }
.LBB0_742:
	v_cvt_scalef32_pk32_f16_fp6 v[0:15], v[64:69], 1.0
	ds_read_b128 v[64:67], v104 offset:3120
	s_mulk_i32 s68, 0x2e00
	v_pk_fma_f16 v68, v71, v0, v106
	v_pk_fma_f16 v69, v71, v1, v107
	v_pk_fma_f16 v106, v71, v2, v108
	v_pk_fma_f16 v107, v71, v3, v109
	v_pk_fma_f16 v108, v71, v4, v110
	v_pk_fma_f16 v109, v71, v5, v111
	v_pk_fma_f16 v110, v71, v6, v112
	v_pk_fma_f16 v111, v71, v7, v113
	v_pk_fma_f16 v112, v71, v8, v114
	v_pk_fma_f16 v113, v71, v9, v115
	v_pk_fma_f16 v114, v71, v10, v116
	v_pk_fma_f16 v115, v71, v11, v117
	v_pk_fma_f16 v116, v71, v12, v118
	v_pk_fma_f16 v117, v71, v13, v119
	v_pk_fma_f16 v104, v71, v14, v105
	v_pk_fma_f16 v70, v71, v15, v70
	v_subrev_u32_e32 v120, s68, v95
	s_waitcnt vmcnt(6)
	s_nop 0
	v_cvt_scalef32_pk32_f16_fp6 v[0:15], v[58:63], 1.0
	s_waitcnt lgkmcnt(0)
	v_pk_fma_f16 v58, v64, v0, v68
	v_pk_fma_f16 v59, v64, v1, v69
	v_pk_fma_f16 v60, v64, v2, v106
	v_pk_fma_f16 v61, v64, v3, v107
	v_pk_fma_f16 v62, v64, v4, v108
	v_pk_fma_f16 v63, v64, v5, v109
	v_pk_fma_f16 v68, v64, v6, v110
	v_pk_fma_f16 v69, v64, v7, v111
	v_pk_fma_f16 v71, v64, v8, v112
	v_pk_fma_f16 v105, v64, v9, v113
	v_pk_fma_f16 v106, v64, v10, v114
	v_pk_fma_f16 v107, v64, v11, v115
	v_pk_fma_f16 v108, v64, v12, v116
	v_pk_fma_f16 v109, v64, v13, v117
	v_pk_fma_f16 v104, v64, v14, v104
	v_pk_fma_f16 v64, v64, v15, v70
	s_waitcnt vmcnt(4)
	s_nop 0
	v_cvt_scalef32_pk32_f16_fp6 v[0:15], v[52:57], 1.0
	v_pk_fma_f16 v52, v65, v0, v58
	v_pk_fma_f16 v53, v65, v1, v59
	v_pk_fma_f16 v54, v65, v2, v60
	v_pk_fma_f16 v55, v65, v3, v61
	v_pk_fma_f16 v56, v65, v4, v62
	v_pk_fma_f16 v57, v65, v5, v63
	v_pk_fma_f16 v58, v65, v6, v68
	v_pk_fma_f16 v59, v65, v7, v69
	v_pk_fma_f16 v60, v65, v8, v71
	v_pk_fma_f16 v61, v65, v9, v105
	v_pk_fma_f16 v62, v65, v10, v106
	v_pk_fma_f16 v63, v65, v11, v107
	v_pk_fma_f16 v68, v65, v12, v108
	v_pk_fma_f16 v69, v65, v13, v109
	v_pk_fma_f16 v70, v65, v14, v104
	v_pk_fma_f16 v64, v65, v15, v64
	s_waitcnt vmcnt(2)
	s_nop 0
	v_cvt_scalef32_pk32_f16_fp6 v[0:15], v[46:51], 1.0
	v_pk_fma_f16 v46, v66, v0, v52
	v_pk_fma_f16 v47, v66, v1, v53
	v_pk_fma_f16 v48, v66, v2, v54
	v_pk_fma_f16 v49, v66, v3, v55
	v_pk_fma_f16 v50, v66, v4, v56
	v_pk_fma_f16 v51, v66, v5, v57
	v_pk_fma_f16 v52, v66, v6, v58
	v_pk_fma_f16 v53, v66, v7, v59
	v_pk_fma_f16 v54, v66, v8, v60
	v_pk_fma_f16 v55, v66, v9, v61
	v_pk_fma_f16 v56, v66, v10, v62
	v_pk_fma_f16 v57, v66, v11, v63
	v_pk_fma_f16 v58, v66, v12, v68
	v_pk_fma_f16 v59, v66, v13, v69
	v_pk_fma_f16 v60, v66, v14, v70
	v_pk_fma_f16 v61, v66, v15, v64
	s_waitcnt vmcnt(0)
	s_nop 0
	v_cvt_scalef32_pk32_f16_fp6 v[0:15], v[40:45], 1.0
	v_pk_fma_f16 v0, v67, v0, v46
	v_pk_fma_f16 v1, v67, v1, v47
	v_pk_fma_f16 v2, v67, v2, v48
	v_pk_fma_f16 v3, v67, v3, v49
	v_pk_fma_f16 v4, v67, v4, v50
	v_pk_fma_f16 v5, v67, v5, v51
	v_pk_fma_f16 v6, v67, v6, v52
	v_pk_fma_f16 v7, v67, v7, v53
	v_pk_fma_f16 v8, v67, v8, v54
	v_pk_fma_f16 v9, v67, v9, v55
	v_pk_fma_f16 v10, v67, v10, v56
	v_pk_fma_f16 v11, v67, v11, v57
	v_pk_fma_f16 v12, v67, v12, v58
	v_pk_fma_f16 v13, v67, v13, v59
	v_pk_fma_f16 v14, v67, v14, v60
	v_pk_fma_f16 v15, v67, v15, v61
	v_permlane32_swap_b32_e32 v0, v8
	v_permlane32_swap_b32_e32 v1, v9
	v_permlane32_swap_b32_e32 v2, v10
	v_permlane32_swap_b32_e32 v3, v11
	v_permlane32_swap_b32_e32 v4, v12
	v_permlane32_swap_b32_e32 v5, v13
	v_permlane32_swap_b32_e32 v6, v14
	v_permlane32_swap_b32_e32 v7, v15
	v_pk_add_f16 v0, v0, v8
	v_pk_add_f16 v1, v1, v9
	v_pk_add_f16 v2, v2, v10
	v_pk_add_f16 v3, v3, v11
	v_pk_add_f16 v4, v4, v12
	v_pk_add_f16 v5, v5, v13
	v_pk_add_f16 v6, v6, v14
	v_pk_add_f16 v7, v7, v15
	v_permlane16_swap_b32_e32 v0, v4
	v_permlane16_swap_b32_e32 v1, v5
	v_permlane16_swap_b32_e32 v2, v6
	v_permlane16_swap_b32_e32 v3, v7
	v_pk_add_f16 v0, v0, v4
	v_pk_add_f16 v1, v1, v5
	v_pk_add_f16 v2, v2, v6
	v_pk_add_f16 v3, v3, v7
	v_cndmask_b32_e64 v4, v2, v0, s[8:9]
	v_cndmask_b32_e64 v0, v0, v2, s[8:9]
	v_cndmask_b32_e64 v2, v3, v1, s[8:9]
	v_cndmask_b32_e64 v1, v1, v3, s[8:9]
	v_mov_b32_dpp v0, v0 row_ror:8 row_mask:0xf bank_mask:0xf bound_ctrl:1
	s_add_i32 s68, s33, s10
	v_mov_b32_dpp v1, v1 row_ror:8 row_mask:0xf bank_mask:0xf bound_ctrl:1
	s_addk_i32 s40, 0x200
	s_add_i32 s11, s11, 1
	s_addk_i32 s10, 0x800
	s_add_i32 s41, s41, 1
	v_pk_add_f16 v0, v4, v0
	v_pk_add_f16 v1, v2, v1
	v_add_u32_e32 v2, s68, v120
	s_cmpk_lg_i32 s40, 0x3000
	ds_write_b64 v2, v[0:1]
	s_cbranch_scc0 .LBB0_678
	.p2align	6
